# isel top-k histogram scan: the sixteen ds_read_b128 per lane issued in a per-lane rotated order so a service group covers all 64 LDS banks (was a 16-way bank conflict)
# speedup vs baseline: 1.0136x; 1.0097x over previous
.LBB0_491:
	v_lshl_add_u32 v2, v221, 8, s34
	v_and_b32_e32 v3, 15, v221
	v_lshlrev_b32_e32 v3, 4, v3
	s_movk_i32 s98, 0xf0
	v_cmp_gt_u32_e64 s[24:25], 32, v221
	v_add_u32_e32 v68, 0, v3
	v_and_or_b32 v68, v68, s98, v2
	ds_read_b128 v[68:71], v68
	v_add_u32_e32 v72, 16, v3
	v_and_or_b32 v72, v72, s98, v2
	ds_read_b128 v[72:75], v72
	v_add_u32_e32 v76, 32, v3
	v_and_or_b32 v76, v76, s98, v2
	ds_read_b128 v[76:79], v76
	v_add_u32_e32 v80, 48, v3
	v_and_or_b32 v80, v80, s98, v2
	ds_read_b128 v[80:83], v80
	v_mov_b32_e32 v67, 0
	s_waitcnt lgkmcnt(3)
	v_add3_u32 v67, v67, v68, v69
	v_add3_u32 v67, v67, v70, v71
	v_add_u32_e32 v68, 64, v3
	v_and_or_b32 v68, v68, s98, v2
	ds_read_b128 v[68:71], v68
	s_waitcnt lgkmcnt(3)
	v_add3_u32 v67, v67, v72, v73
	v_add3_u32 v67, v67, v74, v75
	v_add_u32_e32 v72, 0x50, v3
	v_and_or_b32 v72, v72, s98, v2
	ds_read_b128 v[72:75], v72
	s_waitcnt lgkmcnt(3)
	v_add3_u32 v67, v67, v76, v77
	v_add3_u32 v67, v67, v78, v79
	v_add_u32_e32 v76, 0x60, v3
	v_and_or_b32 v76, v76, s98, v2
	ds_read_b128 v[76:79], v76
	s_waitcnt lgkmcnt(3)
	v_add3_u32 v67, v67, v80, v81
	v_add3_u32 v67, v67, v82, v83
	v_add_u32_e32 v80, 0x70, v3
	v_and_or_b32 v80, v80, s98, v2
	ds_read_b128 v[80:83], v80
	s_waitcnt lgkmcnt(3)
	v_add3_u32 v67, v67, v68, v69
	v_add3_u32 v67, v67, v70, v71
	v_add_u32_e32 v68, 0x80, v3
	v_and_or_b32 v68, v68, s98, v2
	ds_read_b128 v[68:71], v68
	s_waitcnt lgkmcnt(3)
	v_add3_u32 v67, v67, v72, v73
	v_add3_u32 v67, v67, v74, v75
	v_add_u32_e32 v72, 0x90, v3
	v_and_or_b32 v72, v72, s98, v2
	ds_read_b128 v[72:75], v72
	s_waitcnt lgkmcnt(3)
	v_add3_u32 v67, v67, v76, v77
	v_add3_u32 v67, v67, v78, v79
	v_add_u32_e32 v76, 0xa0, v3
	v_and_or_b32 v76, v76, s98, v2
	ds_read_b128 v[76:79], v76
	s_waitcnt lgkmcnt(3)
	v_add3_u32 v67, v67, v80, v81
	v_add3_u32 v67, v67, v82, v83
	v_add_u32_e32 v80, 0xb0, v3
	v_and_or_b32 v80, v80, s98, v2
	ds_read_b128 v[80:83], v80
	s_waitcnt lgkmcnt(3)
	v_add3_u32 v67, v67, v68, v69
	v_add3_u32 v67, v67, v70, v71
	v_add_u32_e32 v68, 0xc0, v3
	v_and_or_b32 v68, v68, s98, v2
	ds_read_b128 v[68:71], v68
	s_waitcnt lgkmcnt(3)
	v_add3_u32 v67, v67, v72, v73
	v_add3_u32 v67, v67, v74, v75
	v_add_u32_e32 v72, 0xd0, v3
	v_and_or_b32 v72, v72, s98, v2
	ds_read_b128 v[72:75], v72
	s_waitcnt lgkmcnt(3)
	v_add3_u32 v67, v67, v76, v77
	v_add3_u32 v67, v67, v78, v79
	v_add_u32_e32 v76, 0xe0, v3
	v_and_or_b32 v76, v76, s98, v2
	ds_read_b128 v[76:79], v76
	s_waitcnt lgkmcnt(3)
	v_add3_u32 v67, v67, v80, v81
	v_add3_u32 v67, v67, v82, v83
	v_add_u32_e32 v80, 0xf0, v3
	v_and_or_b32 v80, v80, s98, v2
	ds_read_b128 v[80:83], v80
	s_waitcnt lgkmcnt(3)
	v_add3_u32 v67, v67, v68, v69
	v_add3_u32 v67, v67, v70, v71
	s_waitcnt lgkmcnt(2)
	v_add3_u32 v67, v67, v72, v73
	v_add3_u32 v67, v67, v74, v75
	s_waitcnt lgkmcnt(1)
	v_add3_u32 v67, v67, v76, v77
	v_add3_u32 v67, v67, v78, v79
	s_waitcnt lgkmcnt(0)
	v_add3_u32 v67, v67, v80, v81
	v_add3_u32 v67, v67, v82, v83
	v_and_b32_e32 v3, 63, v218
	v_cmp_ne_u32_e32 vcc, 63, v3
	v_mov_b32_e32 v2, v67
	s_nop 1
	v_addc_co_u32_e32 v67, vcc, 0, v218, vcc
	v_lshlrev_b32_e32 v67, 2, v67
	ds_bpermute_b32 v68, v67, v2
	v_cmp_eq_u32_e32 vcc, 63, v221
	v_cmp_gt_u32_e64 s[16:17], 62, v3
	v_cmp_gt_u32_e64 s[18:19], 60, v3
	v_cmp_gt_u32_e64 s[20:21], 56, v3
	s_waitcnt lgkmcnt(0)
	v_cndmask_b32_e64 v68, v68, 0, vcc
	v_cndmask_b32_e64 v69, 0, 2, s[16:17]
	v_add_u32_e32 v68, v2, v68
	v_add_lshl_u32 v69, v69, v218, 2
	ds_bpermute_b32 v70, v69, v68
	v_cmp_gt_u32_e64 s[16:17], 62, v221
	v_cmp_gt_u32_e64 s[22:23], 48, v3
	s_movk_i32 s35, 0xff
	s_waitcnt lgkmcnt(0)
	v_cndmask_b32_e64 v70, 0, v70, s[16:17]
	v_add_u32_e32 v68, v68, v70
	v_cndmask_b32_e64 v70, 0, 4, s[18:19]
	v_add_lshl_u32 v70, v70, v218, 2
	ds_bpermute_b32 v71, v70, v68
	v_cmp_gt_u32_e64 s[18:19], 60, v221
	v_cndmask_b32_e64 v3, 0, 16, s[22:23]
	v_add_lshl_u32 v3, v3, v218, 2
	v_cmp_gt_u32_e64 s[22:23], 48, v221
	s_waitcnt lgkmcnt(0)
	v_cndmask_b32_e64 v71, 0, v71, s[18:19]
	v_add_u32_e32 v68, v68, v71
	v_cndmask_b32_e64 v71, 0, 8, s[20:21]
	v_add_lshl_u32 v71, v71, v218, 2
	ds_bpermute_b32 v72, v71, v68
	v_cmp_gt_u32_e64 s[20:21], 56, v221
	s_waitcnt lgkmcnt(0)
	s_nop 0
	v_cndmask_b32_e64 v72, 0, v72, s[20:21]
	v_add_u32_e32 v68, v68, v72
	ds_bpermute_b32 v72, v3, v68
	s_waitcnt lgkmcnt(0)
	v_cndmask_b32_e64 v72, 0, v72, s[22:23]
	v_add_u32_e32 v68, v68, v72
	v_lshl_or_b32 v72, v218, 2, v214
	ds_bpermute_b32 v73, v72, v68
	s_waitcnt lgkmcnt(0)
	v_cndmask_b32_e64 v73, 0, v73, s[24:25]
	v_add_u32_e32 v68, v68, v73
	v_cmp_lt_i32_e64 s[26:27], s35, v68
	s_flbit_i32_b64 s2, s[26:27]
	s_min_u32 s2, s2, 64
	s_sub_i32 s26, 63, s2
	s_lshl_b32 s2, s26, 8
	s_add_i32 s34, s34, s2
	v_lshl_add_u32 v73, v221, 2, s34
	ds_read_b32 v73, v73
	s_mov_b64 s[2:3], 0
	s_waitcnt lgkmcnt(0)
	ds_bpermute_b32 v67, v67, v73
	s_waitcnt lgkmcnt(0)
	v_cndmask_b32_e64 v67, v67, 0, vcc
	v_add_u32_e32 v67, v67, v73
	ds_bpermute_b32 v69, v69, v67
	s_waitcnt lgkmcnt(0)
	v_cndmask_b32_e64 v69, 0, v69, s[16:17]
	v_add_u32_e32 v67, v69, v67
	ds_bpermute_b32 v69, v70, v67
	v_and_b32_e32 v70, 64, v218
	s_lshl_b32 s16, s26, 6
	s_waitcnt lgkmcnt(0)
	v_cndmask_b32_e64 v69, 0, v69, s[18:19]
	v_add_u32_e32 v67, v69, v67
	ds_bpermute_b32 v69, v71, v67
	s_waitcnt lgkmcnt(0)
	v_cndmask_b32_e64 v69, 0, v69, s[20:21]
	v_add_u32_e32 v67, v69, v67
	ds_bpermute_b32 v3, v3, v67
	v_and_or_b32 v69, s26, 63, v70
	v_lshlrev_b32_e32 v69, 2, v69
	ds_bpermute_b32 v2, v69, v2
	ds_bpermute_b32 v68, v69, v68
	s_waitcnt lgkmcnt(2)
	v_cndmask_b32_e64 v3, 0, v3, s[22:23]
	v_add_u32_e32 v3, v3, v67
	ds_bpermute_b32 v67, v72, v3
	s_waitcnt lgkmcnt(1)
	v_sub_u32_e32 v2, v68, v2
	s_waitcnt lgkmcnt(0)
	v_cndmask_b32_e64 v67, 0, v67, s[24:25]
	v_add3_u32 v2, v2, v3, v67
	v_cmp_lt_i32_e32 vcc, s35, v2
	s_flbit_i32_b64 s17, vcc
	s_min_u32 s17, s17, 64
	s_sub_i32 s16, s16, s17
	s_lshl_b32 s16, s16, 20
	s_add_i32 s16, s16, 0x3f00000
	v_mov_b32_e32 v2, 19
	v_mov_b32_e32 v3, s16
